# grid barrier: the first workgroup of each XCD to arrive starts an extra L2 writeback (buffer_wbl2 sc1, not waited on) so the last arriver has less dirty data to flush
# baseline (speedup 1.0000x reference)
.LBB0_153:
	s_or_b64 exec, exec, s[8:9]
	s_waitcnt vmcnt(0)
	s_barrier
	s_mov_b64 s[0:1], exec
	v_readlane_b32 s2, v216, 2
	v_readlane_b32 s3, v216, 3
	s_and_b64 s[2:3], s[0:1], s[2:3]
	s_mov_b64 exec, s[2:3]
	s_cbranch_execz .LBB0_190
	global_atomic_add v1, v[114:115], v119, off sc0
	s_waitcnt vmcnt(0)
	v_mul_hi_u32 v0, v1, v118
	v_mul_lo_u32 v2, v0, v110
	v_sub_u32_e32 v2, v1, v2
	v_cmp_ge_u32_e32 vcc, v2, v110
	v_add_u32_e32 v3, 1, v0
	v_add_u32_e32 v1, 1, v1
	v_cndmask_b32_e32 v0, v0, v3, vcc
	v_sub_u32_e32 v3, v2, v110
	v_cndmask_b32_e32 v2, v2, v3, vcc
	v_cmp_ge_u32_e32 vcc, v2, v110
	v_add_u32_e32 v2, 1, v0
	s_nop 0
	v_cndmask_b32_e32 v0, v0, v2, vcc
	v_mul_lo_u32 v2, v0, v110
	v_add_u32_e32 v2, 1, v2
	v_cmp_eq_u32_e32 vcc, v1, v2
	s_and_b64 vcc, exec, vcc
	s_cbranch_vccz .Lefl_6
	buffer_wbl2 sc1
.Lefl_6:
	v_mad_u64_u32 v[2:3], s[2:3], v110, v0, v[110:111]
	v_cmp_ne_u32_e32 vcc, v1, v2
	s_and_saveexec_b64 s[2:3], vcc
	s_xor_b64 s[2:3], exec, s[2:3]
	s_cbranch_execz .LBB0_168
	s_mov_b32 s24, 0x400001
	s_mov_b64 s[4:5], 0
	s_branch .LBB0_161

.LBB0_408:
	s_waitcnt vmcnt(0)
	s_waitcnt vmcnt(63) expcnt(7) lgkmcnt(15)
	s_barrier
	s_mov_b64 s[0:1], exec
	v_readlane_b32 s2, v216, 2
	v_readlane_b32 s3, v216, 3
	s_and_b64 s[2:3], s[0:1], s[2:3]
	s_mov_b64 exec, s[2:3]
	s_cbranch_execz .LBB0_445
	global_atomic_add v1, v[114:115], v119, off sc0
	s_waitcnt vmcnt(0)
	v_mul_hi_u32 v0, v1, v118
	v_mul_lo_u32 v2, v0, v110
	v_sub_u32_e32 v2, v1, v2
	v_cmp_ge_u32_e32 vcc, v2, v110
	v_add_u32_e32 v3, 1, v0
	v_add_u32_e32 v1, 1, v1
	v_cndmask_b32_e32 v0, v0, v3, vcc
	v_sub_u32_e32 v3, v2, v110
	v_cndmask_b32_e32 v2, v2, v3, vcc
	v_cmp_ge_u32_e32 vcc, v2, v110
	v_add_u32_e32 v2, 1, v0
	s_nop 0
	v_cndmask_b32_e32 v0, v0, v2, vcc
	v_mul_lo_u32 v2, v0, v110
	v_add_u32_e32 v2, 1, v2
	v_cmp_eq_u32_e32 vcc, v1, v2
	s_and_b64 vcc, exec, vcc
	s_cbranch_vccz .Lefl_5
	buffer_wbl2 sc1
.Lefl_5:
	v_mad_u64_u32 v[2:3], s[2:3], v110, v0, v[110:111]
	v_cmp_ne_u32_e32 vcc, v1, v2
	s_and_saveexec_b64 s[2:3], vcc
	s_xor_b64 s[2:3], exec, s[2:3]
	s_cbranch_execz .LBB0_423
	s_mov_b32 s26, 0x400001
	s_mov_b64 s[4:5], 0
	s_branch .LBB0_416

.LBB0_604:
	s_waitcnt vmcnt(0)
	s_barrier
	s_mov_b64 s[0:1], exec
	v_readlane_b32 s2, v216, 2
	v_readlane_b32 s3, v216, 3
	s_and_b64 s[2:3], s[0:1], s[2:3]
	s_mov_b64 exec, s[2:3]
	s_cbranch_execz .LBB0_641
	global_atomic_add v1, v[114:115], v119, off sc0
	s_waitcnt vmcnt(0)
	v_mul_hi_u32 v0, v1, v118
	v_mul_lo_u32 v2, v0, v110
	v_sub_u32_e32 v2, v1, v2
	v_cmp_ge_u32_e32 vcc, v2, v110
	v_add_u32_e32 v3, 1, v0
	v_add_u32_e32 v1, 1, v1
	v_cndmask_b32_e32 v0, v0, v3, vcc
	v_sub_u32_e32 v3, v2, v110
	v_cndmask_b32_e32 v2, v2, v3, vcc
	v_cmp_ge_u32_e32 vcc, v2, v110
	v_add_u32_e32 v2, 1, v0
	s_nop 0
	v_cndmask_b32_e32 v0, v0, v2, vcc
	v_mul_lo_u32 v2, v0, v110
	v_add_u32_e32 v2, 1, v2
	v_cmp_eq_u32_e32 vcc, v1, v2
	s_and_b64 vcc, exec, vcc
	s_cbranch_vccz .Lefl_4
	buffer_wbl2 sc1

.LBB0_999:
	s_waitcnt vmcnt(0)
	s_barrier
	s_mov_b64 s[2:3], exec
	v_readlane_b32 s0, v216, 2
	v_readlane_b32 s1, v216, 3
	s_and_b64 s[0:1], s[2:3], s[0:1]
	s_mov_b64 exec, s[0:1]
	s_cbranch_execz .LBB0_1036
	global_atomic_add v1, v[114:115], v119, off sc0
	s_waitcnt vmcnt(0)
	v_mul_hi_u32 v0, v1, v118
	v_mul_lo_u32 v2, v0, v110
	v_sub_u32_e32 v2, v1, v2
	v_cmp_ge_u32_e32 vcc, v2, v110
	v_add_u32_e32 v3, 1, v0
	v_add_u32_e32 v1, 1, v1
	v_cndmask_b32_e32 v0, v0, v3, vcc
	v_sub_u32_e32 v3, v2, v110
	v_cndmask_b32_e32 v2, v2, v3, vcc
	v_cmp_ge_u32_e32 vcc, v2, v110
	v_add_u32_e32 v2, 1, v0
	s_nop 0
	v_cndmask_b32_e32 v0, v0, v2, vcc
	v_mul_lo_u32 v2, v0, v110
	v_add_u32_e32 v2, 1, v2
	v_cmp_eq_u32_e32 vcc, v1, v2
	s_and_b64 vcc, exec, vcc
	s_cbranch_vccz .Lefl_3
	buffer_wbl2 sc1
.Lefl_3:
	v_mad_u64_u32 v[2:3], s[0:1], v110, v0, v[110:111]
	v_cmp_ne_u32_e32 vcc, v1, v2
	s_and_saveexec_b64 s[0:1], vcc
	s_xor_b64 s[4:5], exec, s[0:1]
	s_cbranch_execz .LBB0_1014
	s_mov_b32 s0, 0x400001
	s_mov_b64 s[6:7], 0
	s_branch .LBB0_1007
